# v146 configuration with the P1 detour threshold at 160 instead of 144
# baseline (speedup 1.0000x reference)
; #define LAS __attribute__((address_space(3)))
; __global__ void __launch_bounds__(512, 2) mk_fwd(Args a) {
;     ...
;         int tid_ = threadIdx.x, bx_ = blockIdx.x; asm volatile("" : "+v"(tid_)); asm volatile("" : "+s"(bx_));
;         const int tid = tid_, lane = tid & 63, wave = tid >> 6, bx = bx_; (void)tid;
;         const int par = layer & 1;
;         unsigned char* ws = a.ws; asm volatile("" : "+s"(ws));
;         bf16_t* WGLU = (bf16_t*)(ws + WS_WGLU); bf16_t* WOUT = (bf16_t*)(ws + WS_WOUT); bf16_t* W1 = (bf16_t*)(ws + WS_W1); bf16_t* W2 = (bf16_t*)(ws + WS_W2);
;         bf16_t* XN = (bf16_t*)(ws + WS_XN); bf16_t* HID = (bf16_t*)(ws + WS_HID); bf16_t* MIX = (bf16_t*)(ws + WS_MIX); bf16_t* YB = (bf16_t*)(ws + WS_Y); bf16_t* UB = (bf16_t*)(ws + WS_UB);
;         float* PART = (float*)(ws + WS_PART);
;         bf16_t* WIN = (bf16_t*)(ws + (par ? WS_WIN2 : WS_WIN)); bf16_t* WINN = (bf16_t*)(ws + (par ? WS_WIN : WS_WIN2));
;         for (int rp = 0; rp < REP_P1; ++rp) {
;             pg8::Gemm g{XN, WIN, DM, DM, DM, 0, 0}; pg8::StaticOrder S; S.init(NTOK, INW, G, bx);
;             LAS float* rsl = (LAS float*)(lds + 131072);
;             Unit u0, u1; int pm0 = 0;
;             pg8::RsPre pre{PART, rsl, 0, 0, 0};
;             if (S.next(0, u0)) { pm0 = u0.pm; const bool two = S.next(1, u1); pre.pm0 = u0.pm; pre.pm1 = two ? u1.pm : u0.pm; pre.ntab = two ? 2 : 1; }
;             EpiInProj E{rsl, pm0, (bf16_t*)(ws + WS_Q), (bf16_t*)(ws + WS_K), (bf16_t*)(ws + WS_V), UB};
;             pg8::gemm_phase<EpiInProj, pg8::StaticOrder, true, true, pg8::RsPre>(lds, g, S, E, pre);
.LBB0_161:
	v_readlane_b32 s0, v254, 53
	s_and_b32 s15, s0, 1
	s_add_u32 s54, s92, 0x3800000
	s_addc_u32 s55, s93, 0
	s_add_u32 s56, s92, 0x5800000
	s_addc_u32 s57, s93, 0
	s_add_u32 s44, s92, 0x7000000
	s_addc_u32 s45, s93, 0
	s_add_u32 s62, s92, 0xd800000
	s_addc_u32 s63, s93, 0
	s_cmp_eq_u32 s15, 0
	s_cselect_b64 s[64:65], -1, 0
	s_and_b64 vcc, exec, s[38:39]
	s_mov_b32 s18, s42
	v_readlane_b32 s1, v254, 54
	s_cbranch_vccnz .LBB0_307
	v_readlane_b32 vcc_lo, v255, 56
	s_cmp_lg_u32 vcc_lo, 0
	s_cbranch_scc1 .Ldt_cont
	s_cmpk_lt_i32 s49, 160
	s_cbranch_scc1 .Ldt_cont
	s_waitcnt lgkmcnt(0)
	v_writelane_b32 v255, 1, 56
	s_branch .LBB0_307
